# PEER epilogue: counted waits per token (each token's math starts when its own four residual loads have landed) + v ring tail trim
# speedup vs baseline: 1.0018x; 1.0018x over previous
; __device__ __forceinline__ void peer_tile(const Args& A, LAS unsigned char* lds, int tile) {
;     ...
;         for (int tk = 0; tk < 4; ++tk) {
;             const size_t m = (size_t)tile * 64 + tb + tk; const int b = (int)(m >> 11);
;             float* orow = A.out + m * 1024 + 16 * lane;
;             const float* g2 = MOD + b * 6144 + 5120 + 16 * lane;
;             f32x4 xv[4]; float ss = 0.f;
; #pragma unroll
;             for (int j = 0; j < 4; ++j) { const f32x4 x1 = *(const f32x4*)(orow + 4 * j), gg = *(const f32x4*)(g2 + 4 * j);
;                 const f32x4 pe = (f32x4){oacc[tk][2 * j][0], oacc[tk][2 * j][1], oacc[tk][2 * j + 1][0], oacc[tk][2 * j + 1][1]};
;                 xv[j] = x1 + gg * pe; ss += (xv[j][0] * xv[j][0] + xv[j][1] * xv[j][1]) + (xv[j][2] * xv[j][2] + xv[j][3] * xv[j][3]); }
.LV_done:
	s_waitcnt lgkmcnt(0)
	global_load_dwordx4 v[192:195], v246, s[82:83]
	global_load_dwordx4 v[196:199], v246, s[82:83] offset:16
	global_load_dwordx4 v[200:203], v246, s[82:83] offset:32
	global_load_dwordx4 v[204:207], v246, s[82:83] offset:48
	global_load_dwordx4 v[216:219], v246, s[46:47]
	global_load_dwordx4 v[220:223], v246, s[46:47] offset:16
	global_load_dwordx4 v[224:227], v246, s[46:47] offset:32
	global_load_dwordx4 v[228:231], v246, s[46:47] offset:48
	s_add_i32 s0, s77, 0
	s_lshl_b32 s0, s0, 12
	s_add_u32 s24, s48, s0
	s_addc_u32 s25, s49, 0
	s_add_i32 s0, s77, 1
	s_lshl_b32 s0, s0, 12
	s_add_u32 s26, s48, s0
	s_addc_u32 s27, s49, 0
	s_add_i32 s0, s77, 2
	s_lshl_b32 s0, s0, 12
	s_add_u32 s28, s48, s0
	s_addc_u32 s29, s49, 0
	s_add_i32 s0, s77, 3
	s_lshl_b32 s0, s0, 12
	s_add_u32 s30, s48, s0
	s_addc_u32 s31, s49, 0
	global_load_dwordx4 v[128:131], v246, s[24:25]
	global_load_dwordx4 v[132:135], v246, s[24:25] offset:16
	global_load_dwordx4 v[136:139], v246, s[24:25] offset:32
	global_load_dwordx4 v[140:143], v246, s[24:25] offset:48
	global_load_dwordx4 v[144:147], v246, s[26:27]
	global_load_dwordx4 v[148:151], v246, s[26:27] offset:16
	global_load_dwordx4 v[152:155], v246, s[26:27] offset:32
	global_load_dwordx4 v[156:159], v246, s[26:27] offset:48
	global_load_dwordx4 v[160:163], v246, s[28:29]
	global_load_dwordx4 v[164:167], v246, s[28:29] offset:16
	global_load_dwordx4 v[168:171], v246, s[28:29] offset:32
	global_load_dwordx4 v[172:175], v246, s[28:29] offset:48
	global_load_dwordx4 v[176:179], v246, s[30:31]
	global_load_dwordx4 v[180:183], v246, s[30:31] offset:16
	global_load_dwordx4 v[184:187], v246, s[30:31] offset:32
	global_load_dwordx4 v[188:191], v246, s[30:31] offset:48
	s_waitcnt vmcnt(12)
	v_pk_fma_f32 v[128:129], v[0:1], v[192:193], v[128:129]
	v_pk_fma_f32 v[130:131], v[2:3], v[194:195], v[130:131]
	v_pk_fma_f32 v[132:133], v[4:5], v[196:197], v[132:133]
	v_pk_fma_f32 v[134:135], v[6:7], v[198:199], v[134:135]
	v_pk_fma_f32 v[136:137], v[8:9], v[200:201], v[136:137]
	v_pk_fma_f32 v[138:139], v[10:11], v[202:203], v[138:139]
	v_pk_fma_f32 v[140:141], v[12:13], v[204:205], v[140:141]
	v_pk_fma_f32 v[142:143], v[14:15], v[206:207], v[142:143]
	v_pk_mul_f32 v[248:249], v[128:129], v[128:129]
	v_pk_fma_f32 v[248:249], v[130:131], v[130:131], v[248:249]
	v_pk_fma_f32 v[248:249], v[132:133], v[132:133], v[248:249]
	v_pk_fma_f32 v[248:249], v[134:135], v[134:135], v[248:249]
	v_pk_fma_f32 v[248:249], v[136:137], v[136:137], v[248:249]
	v_pk_fma_f32 v[248:249], v[138:139], v[138:139], v[248:249]
	v_pk_fma_f32 v[248:249], v[140:141], v[140:141], v[248:249]
	v_pk_fma_f32 v[248:249], v[142:143], v[142:143], v[248:249]
	s_waitcnt vmcnt(8)
	v_pk_fma_f32 v[144:145], v[16:17], v[192:193], v[144:145]
	v_pk_fma_f32 v[146:147], v[18:19], v[194:195], v[146:147]
	v_pk_fma_f32 v[148:149], v[20:21], v[196:197], v[148:149]
	v_pk_fma_f32 v[150:151], v[22:23], v[198:199], v[150:151]
	v_pk_fma_f32 v[152:153], v[24:25], v[200:201], v[152:153]
	v_pk_fma_f32 v[154:155], v[26:27], v[202:203], v[154:155]
	v_pk_fma_f32 v[156:157], v[28:29], v[204:205], v[156:157]
	v_pk_fma_f32 v[158:159], v[30:31], v[206:207], v[158:159]
	v_pk_mul_f32 v[250:251], v[144:145], v[144:145]
	v_pk_fma_f32 v[250:251], v[146:147], v[146:147], v[250:251]
	v_pk_fma_f32 v[250:251], v[148:149], v[148:149], v[250:251]
	v_pk_fma_f32 v[250:251], v[150:151], v[150:151], v[250:251]
	v_pk_fma_f32 v[250:251], v[152:153], v[152:153], v[250:251]
	v_pk_fma_f32 v[250:251], v[154:155], v[154:155], v[250:251]
	v_pk_fma_f32 v[250:251], v[156:157], v[156:157], v[250:251]
	v_pk_fma_f32 v[250:251], v[158:159], v[158:159], v[250:251]
	s_waitcnt vmcnt(4)
	v_pk_fma_f32 v[160:161], v[32:33], v[192:193], v[160:161]
	v_pk_fma_f32 v[162:163], v[34:35], v[194:195], v[162:163]
	v_pk_fma_f32 v[164:165], v[36:37], v[196:197], v[164:165]
	v_pk_fma_f32 v[166:167], v[38:39], v[198:199], v[166:167]
	v_pk_fma_f32 v[168:169], v[40:41], v[200:201], v[168:169]
	v_pk_fma_f32 v[170:171], v[42:43], v[202:203], v[170:171]
	v_pk_fma_f32 v[172:173], v[44:45], v[204:205], v[172:173]
	v_pk_fma_f32 v[174:175], v[46:47], v[206:207], v[174:175]
	v_pk_mul_f32 v[252:253], v[160:161], v[160:161]
	v_pk_fma_f32 v[252:253], v[162:163], v[162:163], v[252:253]
	v_pk_fma_f32 v[252:253], v[164:165], v[164:165], v[252:253]
	v_pk_fma_f32 v[252:253], v[166:167], v[166:167], v[252:253]
	v_pk_fma_f32 v[252:253], v[168:169], v[168:169], v[252:253]
	v_pk_fma_f32 v[252:253], v[170:171], v[170:171], v[252:253]
	v_pk_fma_f32 v[252:253], v[172:173], v[172:173], v[252:253]
	v_pk_fma_f32 v[252:253], v[174:175], v[174:175], v[252:253]
	s_waitcnt vmcnt(0)
; __device__ __forceinline__ float wave_sum(float v) {
;     { const auto r = __builtin_amdgcn_permlane32_swap(__float_as_uint(v), __float_as_uint(v), false, false); v = __uint_as_float(r[0]) + __uint_as_float(r[1]); }
;     { const auto r = __builtin_amdgcn_permlane16_swap(__float_as_uint(v), __float_as_uint(v), false, false); v = __uint_as_float(r[0]) + __uint_as_float(r[1]); }
;     v += __int_as_float(__builtin_amdgcn_mov_dpp(__float_as_int(v), 0xB1, 0xF, 0xF, true));
;     v += __int_as_float(__builtin_amdgcn_mov_dpp(__float_as_int(v), 0x4E, 0xF, 0xF, true));
;     v += __int_as_float(__builtin_amdgcn_mov_dpp(__float_as_int(v), 0x141, 0xF, 0xF, true));
;     v += __int_as_float(__builtin_amdgcn_mov_dpp(__float_as_int(v), 0x140, 0xF, 0xF, true));
;     return v;
; __device__ __forceinline__ void peer_tile(const Args& A, LAS unsigned char* lds, int tile) {
;     ...
;             for (int j = 0; j < 4; ++j) { const f32x4 x1 = *(const f32x4*)(orow + 4 * j), gg = *(const f32x4*)(g2 + 4 * j);
;                 const f32x4 pe = (f32x4){oacc[tk][2 * j][0], oacc[tk][2 * j][1], oacc[tk][2 * j + 1][0], oacc[tk][2 * j + 1][1]};
;                 xv[j] = x1 + gg * pe; ss += (xv[j][0] * xv[j][0] + xv[j][1] * xv[j][1]) + (xv[j][2] * xv[j][2] + xv[j][3] * xv[j][3]); }
;             const float rstd = rsqrtf(wave_sum(ss) * (1.f / 1024.f) + 1e-6f);
; #pragma unroll
;             for (int j = 0; j < 4; ++j) { const f32x4 fg = *(const f32x4*)(A.final_g + 16 * lane + 4 * j); *(f32x4*)(orow + 4 * j) = xv[j] * rstd * fg; }
	v_pk_fma_f32 v[176:177], v[48:49], v[192:193], v[176:177]
	v_pk_fma_f32 v[178:179], v[50:51], v[194:195], v[178:179]
	v_pk_fma_f32 v[180:181], v[52:53], v[196:197], v[180:181]
	v_pk_fma_f32 v[182:183], v[54:55], v[198:199], v[182:183]
	v_pk_fma_f32 v[184:185], v[56:57], v[200:201], v[184:185]
	v_pk_fma_f32 v[186:187], v[58:59], v[202:203], v[186:187]
	v_pk_fma_f32 v[188:189], v[60:61], v[204:205], v[188:189]
	v_pk_fma_f32 v[190:191], v[62:63], v[206:207], v[190:191]
	v_pk_mul_f32 v[254:255], v[176:177], v[176:177]
	v_pk_fma_f32 v[254:255], v[178:179], v[178:179], v[254:255]
	v_pk_fma_f32 v[254:255], v[180:181], v[180:181], v[254:255]
	v_pk_fma_f32 v[254:255], v[182:183], v[182:183], v[254:255]
	v_pk_fma_f32 v[254:255], v[184:185], v[184:185], v[254:255]
	v_pk_fma_f32 v[254:255], v[186:187], v[186:187], v[254:255]
	v_pk_fma_f32 v[254:255], v[188:189], v[188:189], v[254:255]
	v_pk_fma_f32 v[254:255], v[190:191], v[190:191], v[254:255]
	s_add_i32 s0, s77, 4
	s_lshl_b32 s0, s0, 12
	s_add_u32 s56, s48, s0
	s_addc_u32 s57, s49, 0
	s_add_i32 s0, s77, 5
	s_lshl_b32 s0, s0, 12
	s_add_u32 s58, s48, s0
	s_addc_u32 s59, s49, 0
	s_add_i32 s0, s77, 6
	s_lshl_b32 s0, s0, 12
	s_add_u32 s60, s48, s0
	s_addc_u32 s61, s49, 0
	s_add_i32 s0, s77, 7
	s_lshl_b32 s0, s0, 12
	s_add_u32 s62, s48, s0
	s_addc_u32 s63, s49, 0
	global_load_dwordx4 v[0:3], v246, s[56:57]
	global_load_dwordx4 v[4:7], v246, s[56:57] offset:16
	global_load_dwordx4 v[8:11], v246, s[56:57] offset:32
	global_load_dwordx4 v[12:15], v246, s[56:57] offset:48
	global_load_dwordx4 v[16:19], v246, s[58:59]
	global_load_dwordx4 v[20:23], v246, s[58:59] offset:16
	global_load_dwordx4 v[24:27], v246, s[58:59] offset:32
	global_load_dwordx4 v[28:31], v246, s[58:59] offset:48
	global_load_dwordx4 v[32:35], v246, s[60:61]
	global_load_dwordx4 v[36:39], v246, s[60:61] offset:16
	global_load_dwordx4 v[40:43], v246, s[60:61] offset:32
	global_load_dwordx4 v[44:47], v246, s[60:61] offset:48
	global_load_dwordx4 v[48:51], v246, s[62:63]
	global_load_dwordx4 v[52:55], v246, s[62:63] offset:16
	global_load_dwordx4 v[56:59], v246, s[62:63] offset:32
	global_load_dwordx4 v[60:63], v246, s[62:63] offset:48
	v_add_f32_e32 v248, v248, v249
	v_add_f32_e32 v250, v250, v251
	v_add_f32_e32 v252, v252, v253
	v_add_f32_e32 v254, v254, v255
	v_mov_b32_e32 v249, v248
	v_mov_b32_e32 v251, v250
	v_mov_b32_e32 v253, v252
	v_mov_b32_e32 v255, v254
	v_permlane32_swap_b32_e32 v248, v249
	v_permlane32_swap_b32_e32 v250, v251
	v_permlane32_swap_b32_e32 v252, v253
	v_permlane32_swap_b32_e32 v254, v255
	v_add_f32_e32 v248, v248, v249
	v_add_f32_e32 v250, v250, v251
	v_add_f32_e32 v252, v252, v253
	v_add_f32_e32 v254, v254, v255
	v_mov_b32_e32 v249, v248
	v_mov_b32_e32 v251, v250
	v_mov_b32_e32 v253, v252
	v_mov_b32_e32 v255, v254
	v_permlane16_swap_b32_e32 v248, v249
	v_permlane16_swap_b32_e32 v250, v251
	v_permlane16_swap_b32_e32 v252, v253
	v_permlane16_swap_b32_e32 v254, v255
	v_add_f32_e32 v248, v248, v249
	v_add_f32_e32 v250, v250, v251
	v_add_f32_e32 v252, v252, v253
	v_add_f32_e32 v254, v254, v255
	v_add_f32_dpp v248, v248, v248 quad_perm:[1,0,3,2] row_mask:0xf bank_mask:0xf bound_ctrl:1
	v_add_f32_dpp v250, v250, v250 quad_perm:[1,0,3,2] row_mask:0xf bank_mask:0xf bound_ctrl:1
	v_add_f32_dpp v252, v252, v252 quad_perm:[1,0,3,2] row_mask:0xf bank_mask:0xf bound_ctrl:1
	v_add_f32_dpp v254, v254, v254 quad_perm:[1,0,3,2] row_mask:0xf bank_mask:0xf bound_ctrl:1
	v_add_f32_dpp v248, v248, v248 quad_perm:[2,3,0,1] row_mask:0xf bank_mask:0xf bound_ctrl:1
	v_add_f32_dpp v250, v250, v250 quad_perm:[2,3,0,1] row_mask:0xf bank_mask:0xf bound_ctrl:1
	v_add_f32_dpp v252, v252, v252 quad_perm:[2,3,0,1] row_mask:0xf bank_mask:0xf bound_ctrl:1
	v_add_f32_dpp v254, v254, v254 quad_perm:[2,3,0,1] row_mask:0xf bank_mask:0xf bound_ctrl:1
	v_add_f32_dpp v248, v248, v248 row_half_mirror row_mask:0xf bank_mask:0xf bound_ctrl:1
	v_add_f32_dpp v250, v250, v250 row_half_mirror row_mask:0xf bank_mask:0xf bound_ctrl:1
	v_add_f32_dpp v252, v252, v252 row_half_mirror row_mask:0xf bank_mask:0xf bound_ctrl:1
	v_add_f32_dpp v254, v254, v254 row_half_mirror row_mask:0xf bank_mask:0xf bound_ctrl:1
	v_add_f32_dpp v248, v248, v248 row_mirror row_mask:0xf bank_mask:0xf bound_ctrl:1
	v_add_f32_dpp v250, v250, v250 row_mirror row_mask:0xf bank_mask:0xf bound_ctrl:1
	v_add_f32_dpp v252, v252, v252 row_mirror row_mask:0xf bank_mask:0xf bound_ctrl:1
	v_add_f32_dpp v254, v254, v254 row_mirror row_mask:0xf bank_mask:0xf bound_ctrl:1
	v_fmamk_f32 v248, v248, 0x3a800000, v243
	v_fmamk_f32 v250, v250, 0x3a800000, v243
	v_fmamk_f32 v252, v252, 0x3a800000, v243
	v_fmamk_f32 v254, v254, 0x3a800000, v243
	v_rsq_f32_e32 v248, v248
	v_rsq_f32_e32 v250, v250
	v_rsq_f32_e32 v252, v252
	v_rsq_f32_e32 v254, v254
	s_nop 0
	v_pk_mul_f32 v[128:129], v[128:129], v[248:249] op_sel_hi:[1,0]
	v_pk_mul_f32 v[130:131], v[130:131], v[248:249] op_sel_hi:[1,0]
	v_pk_mul_f32 v[132:133], v[132:133], v[248:249] op_sel_hi:[1,0]
	v_pk_mul_f32 v[134:135], v[134:135], v[248:249] op_sel_hi:[1,0]
	v_pk_mul_f32 v[136:137], v[136:137], v[248:249] op_sel_hi:[1,0]
	v_pk_mul_f32 v[138:139], v[138:139], v[248:249] op_sel_hi:[1,0]
	v_pk_mul_f32 v[140:141], v[140:141], v[248:249] op_sel_hi:[1,0]
	v_pk_mul_f32 v[142:143], v[142:143], v[248:249] op_sel_hi:[1,0]
	v_pk_mul_f32 v[128:129], v[216:217], v[128:129]
	v_pk_mul_f32 v[130:131], v[218:219], v[130:131]
	v_pk_mul_f32 v[132:133], v[220:221], v[132:133]
	v_pk_mul_f32 v[134:135], v[222:223], v[134:135]
	v_pk_mul_f32 v[136:137], v[224:225], v[136:137]
	v_pk_mul_f32 v[138:139], v[226:227], v[138:139]
	v_pk_mul_f32 v[140:141], v[228:229], v[140:141]
; __device__ __forceinline__ void peer_tile(const Args& A, LAS unsigned char* lds, int tile) {
;     ...
;             for (int j = 0; j < 4; ++j) { const f32x4 x1 = *(const f32x4*)(orow + 4 * j), gg = *(const f32x4*)(g2 + 4 * j);
;                 const f32x4 pe = (f32x4){oacc[tk][2 * j][0], oacc[tk][2 * j][1], oacc[tk][2 * j + 1][0], oacc[tk][2 * j + 1][1]};
;                 xv[j] = x1 + gg * pe; ss += (xv[j][0] * xv[j][0] + xv[j][1] * xv[j][1]) + (xv[j][2] * xv[j][2] + xv[j][3] * xv[j][3]); }
;             const float rstd = rsqrtf(wave_sum(ss) * (1.f / 1024.f) + 1e-6f);
; #pragma unroll
;             for (int j = 0; j < 4; ++j) { const f32x4 fg = *(const f32x4*)(A.final_g + 16 * lane + 4 * j); *(f32x4*)(orow + 4 * j) = xv[j] * rstd * fg; }
	v_pk_mul_f32 v[142:143], v[230:231], v[142:143]
	global_store_dwordx4 v246, v[128:131], s[24:25]
	global_store_dwordx4 v246, v[132:135], s[24:25] offset:16
	global_store_dwordx4 v246, v[136:139], s[24:25] offset:32
	global_store_dwordx4 v246, v[140:143], s[24:25] offset:48
	v_pk_mul_f32 v[144:145], v[144:145], v[250:251] op_sel_hi:[1,0]
	v_pk_mul_f32 v[146:147], v[146:147], v[250:251] op_sel_hi:[1,0]
	v_pk_mul_f32 v[148:149], v[148:149], v[250:251] op_sel_hi:[1,0]
	v_pk_mul_f32 v[150:151], v[150:151], v[250:251] op_sel_hi:[1,0]
	v_pk_mul_f32 v[152:153], v[152:153], v[250:251] op_sel_hi:[1,0]
	v_pk_mul_f32 v[154:155], v[154:155], v[250:251] op_sel_hi:[1,0]
	v_pk_mul_f32 v[156:157], v[156:157], v[250:251] op_sel_hi:[1,0]
	v_pk_mul_f32 v[158:159], v[158:159], v[250:251] op_sel_hi:[1,0]
	v_pk_mul_f32 v[144:145], v[216:217], v[144:145]
	v_pk_mul_f32 v[146:147], v[218:219], v[146:147]
	v_pk_mul_f32 v[148:149], v[220:221], v[148:149]
	v_pk_mul_f32 v[150:151], v[222:223], v[150:151]
	v_pk_mul_f32 v[152:153], v[224:225], v[152:153]
	v_pk_mul_f32 v[154:155], v[226:227], v[154:155]
	v_pk_mul_f32 v[156:157], v[228:229], v[156:157]
	v_pk_mul_f32 v[158:159], v[230:231], v[158:159]
	global_store_dwordx4 v246, v[144:147], s[26:27]
	global_store_dwordx4 v246, v[148:151], s[26:27] offset:16
	global_store_dwordx4 v246, v[152:155], s[26:27] offset:32
	global_store_dwordx4 v246, v[156:159], s[26:27] offset:48
	v_pk_mul_f32 v[160:161], v[160:161], v[252:253] op_sel_hi:[1,0]
	v_pk_mul_f32 v[162:163], v[162:163], v[252:253] op_sel_hi:[1,0]
	v_pk_mul_f32 v[164:165], v[164:165], v[252:253] op_sel_hi:[1,0]
	v_pk_mul_f32 v[166:167], v[166:167], v[252:253] op_sel_hi:[1,0]
	v_pk_mul_f32 v[168:169], v[168:169], v[252:253] op_sel_hi:[1,0]
	v_pk_mul_f32 v[170:171], v[170:171], v[252:253] op_sel_hi:[1,0]
	v_pk_mul_f32 v[172:173], v[172:173], v[252:253] op_sel_hi:[1,0]
	v_pk_mul_f32 v[174:175], v[174:175], v[252:253] op_sel_hi:[1,0]
	v_pk_mul_f32 v[160:161], v[216:217], v[160:161]
	v_pk_mul_f32 v[162:163], v[218:219], v[162:163]
	v_pk_mul_f32 v[164:165], v[220:221], v[164:165]
	v_pk_mul_f32 v[166:167], v[222:223], v[166:167]
	v_pk_mul_f32 v[168:169], v[224:225], v[168:169]
	v_pk_mul_f32 v[170:171], v[226:227], v[170:171]
	v_pk_mul_f32 v[172:173], v[228:229], v[172:173]
	v_pk_mul_f32 v[174:175], v[230:231], v[174:175]
	global_store_dwordx4 v246, v[160:163], s[28:29]
	global_store_dwordx4 v246, v[164:167], s[28:29] offset:16
	global_store_dwordx4 v246, v[168:171], s[28:29] offset:32
	global_store_dwordx4 v246, v[172:175], s[28:29] offset:48
	v_pk_mul_f32 v[176:177], v[176:177], v[254:255] op_sel_hi:[1,0]
	v_pk_mul_f32 v[178:179], v[178:179], v[254:255] op_sel_hi:[1,0]
	v_pk_mul_f32 v[180:181], v[180:181], v[254:255] op_sel_hi:[1,0]
	v_pk_mul_f32 v[182:183], v[182:183], v[254:255] op_sel_hi:[1,0]
	v_pk_mul_f32 v[184:185], v[184:185], v[254:255] op_sel_hi:[1,0]
	v_pk_mul_f32 v[186:187], v[186:187], v[254:255] op_sel_hi:[1,0]
	v_pk_mul_f32 v[188:189], v[188:189], v[254:255] op_sel_hi:[1,0]
	v_pk_mul_f32 v[190:191], v[190:191], v[254:255] op_sel_hi:[1,0]
	v_pk_mul_f32 v[176:177], v[216:217], v[176:177]
	v_pk_mul_f32 v[178:179], v[218:219], v[178:179]
	v_pk_mul_f32 v[180:181], v[220:221], v[180:181]
	v_pk_mul_f32 v[182:183], v[222:223], v[182:183]
	v_pk_mul_f32 v[184:185], v[224:225], v[184:185]
	v_pk_mul_f32 v[186:187], v[226:227], v[186:187]
	v_pk_mul_f32 v[188:189], v[228:229], v[188:189]
	v_pk_mul_f32 v[190:191], v[230:231], v[190:191]
	global_store_dwordx4 v246, v[176:179], s[30:31]
	global_store_dwordx4 v246, v[180:183], s[30:31] offset:16
	global_store_dwordx4 v246, v[184:187], s[30:31] offset:32
	global_store_dwordx4 v246, v[188:191], s[30:31] offset:48
	s_nop 1
	s_waitcnt vmcnt(28)
	v_pk_fma_f32 v[0:1], v[64:65], v[192:193], v[0:1]
	v_pk_fma_f32 v[2:3], v[66:67], v[194:195], v[2:3]
	v_pk_fma_f32 v[4:5], v[68:69], v[196:197], v[4:5]
	v_pk_fma_f32 v[6:7], v[70:71], v[198:199], v[6:7]
	v_pk_fma_f32 v[8:9], v[72:73], v[200:201], v[8:9]
	v_pk_fma_f32 v[10:11], v[74:75], v[202:203], v[10:11]
	v_pk_fma_f32 v[12:13], v[76:77], v[204:205], v[12:13]
	v_pk_fma_f32 v[14:15], v[78:79], v[206:207], v[14:15]
	v_pk_mul_f32 v[248:249], v[0:1], v[0:1]
	v_pk_fma_f32 v[248:249], v[2:3], v[2:3], v[248:249]
	v_pk_fma_f32 v[248:249], v[4:5], v[4:5], v[248:249]
	v_pk_fma_f32 v[248:249], v[6:7], v[6:7], v[248:249]
	v_pk_fma_f32 v[248:249], v[8:9], v[8:9], v[248:249]
	v_pk_fma_f32 v[248:249], v[10:11], v[10:11], v[248:249]
	v_pk_fma_f32 v[248:249], v[12:13], v[12:13], v[248:249]
	v_pk_fma_f32 v[248:249], v[14:15], v[14:15], v[248:249]
	s_waitcnt vmcnt(24)
	v_pk_fma_f32 v[16:17], v[80:81], v[192:193], v[16:17]
	v_pk_fma_f32 v[18:19], v[82:83], v[194:195], v[18:19]
	v_pk_fma_f32 v[20:21], v[84:85], v[196:197], v[20:21]
	v_pk_fma_f32 v[22:23], v[86:87], v[198:199], v[22:23]
	v_pk_fma_f32 v[24:25], v[88:89], v[200:201], v[24:25]
	v_pk_fma_f32 v[26:27], v[90:91], v[202:203], v[26:27]
	v_pk_fma_f32 v[28:29], v[92:93], v[204:205], v[28:29]
	v_pk_fma_f32 v[30:31], v[94:95], v[206:207], v[30:31]
	v_pk_mul_f32 v[250:251], v[16:17], v[16:17]
	v_pk_fma_f32 v[250:251], v[18:19], v[18:19], v[250:251]
	v_pk_fma_f32 v[250:251], v[20:21], v[20:21], v[250:251]
	v_pk_fma_f32 v[250:251], v[22:23], v[22:23], v[250:251]
	v_pk_fma_f32 v[250:251], v[24:25], v[24:25], v[250:251]
	v_pk_fma_f32 v[250:251], v[26:27], v[26:27], v[250:251]
	v_pk_fma_f32 v[250:251], v[28:29], v[28:29], v[250:251]
	v_pk_fma_f32 v[250:251], v[30:31], v[30:31], v[250:251]
	s_waitcnt vmcnt(20)
; __device__ __forceinline__ float wave_sum(float v) {
;     { const auto r = __builtin_amdgcn_permlane32_swap(__float_as_uint(v), __float_as_uint(v), false, false); v = __uint_as_float(r[0]) + __uint_as_float(r[1]); }
;     { const auto r = __builtin_amdgcn_permlane16_swap(__float_as_uint(v), __float_as_uint(v), false, false); v = __uint_as_float(r[0]) + __uint_as_float(r[1]); }
;     v += __int_as_float(__builtin_amdgcn_mov_dpp(__float_as_int(v), 0xB1, 0xF, 0xF, true));
;     v += __int_as_float(__builtin_amdgcn_mov_dpp(__float_as_int(v), 0x4E, 0xF, 0xF, true));
;     v += __int_as_float(__builtin_amdgcn_mov_dpp(__float_as_int(v), 0x141, 0xF, 0xF, true));
;     v += __int_as_float(__builtin_amdgcn_mov_dpp(__float_as_int(v), 0x140, 0xF, 0xF, true));
;     return v;
; __device__ __forceinline__ void peer_tile(const Args& A, LAS unsigned char* lds, int tile) {
;     ...
;             for (int j = 0; j < 4; ++j) { const f32x4 x1 = *(const f32x4*)(orow + 4 * j), gg = *(const f32x4*)(g2 + 4 * j);
;                 const f32x4 pe = (f32x4){oacc[tk][2 * j][0], oacc[tk][2 * j][1], oacc[tk][2 * j + 1][0], oacc[tk][2 * j + 1][1]};
;                 xv[j] = x1 + gg * pe; ss += (xv[j][0] * xv[j][0] + xv[j][1] * xv[j][1]) + (xv[j][2] * xv[j][2] + xv[j][3] * xv[j][3]); }
;             const float rstd = rsqrtf(wave_sum(ss) * (1.f / 1024.f) + 1e-6f);
	v_pk_fma_f32 v[32:33], v[96:97], v[192:193], v[32:33]
	v_pk_fma_f32 v[34:35], v[98:99], v[194:195], v[34:35]
	v_pk_fma_f32 v[36:37], v[100:101], v[196:197], v[36:37]
	v_pk_fma_f32 v[38:39], v[102:103], v[198:199], v[38:39]
	v_pk_fma_f32 v[40:41], v[104:105], v[200:201], v[40:41]
	v_pk_fma_f32 v[42:43], v[106:107], v[202:203], v[42:43]
	v_pk_fma_f32 v[44:45], v[108:109], v[204:205], v[44:45]
	v_pk_fma_f32 v[46:47], v[110:111], v[206:207], v[46:47]
	v_pk_mul_f32 v[252:253], v[32:33], v[32:33]
	v_pk_fma_f32 v[252:253], v[34:35], v[34:35], v[252:253]
	v_pk_fma_f32 v[252:253], v[36:37], v[36:37], v[252:253]
	v_pk_fma_f32 v[252:253], v[38:39], v[38:39], v[252:253]
	v_pk_fma_f32 v[252:253], v[40:41], v[40:41], v[252:253]
	v_pk_fma_f32 v[252:253], v[42:43], v[42:43], v[252:253]
	v_pk_fma_f32 v[252:253], v[44:45], v[44:45], v[252:253]
	v_pk_fma_f32 v[252:253], v[46:47], v[46:47], v[252:253]
	s_waitcnt vmcnt(16)
	v_pk_fma_f32 v[48:49], v[112:113], v[192:193], v[48:49]
	v_pk_fma_f32 v[50:51], v[114:115], v[194:195], v[50:51]
	v_pk_fma_f32 v[52:53], v[116:117], v[196:197], v[52:53]
	v_pk_fma_f32 v[54:55], v[118:119], v[198:199], v[54:55]
	v_pk_fma_f32 v[56:57], v[120:121], v[200:201], v[56:57]
	v_pk_fma_f32 v[58:59], v[122:123], v[202:203], v[58:59]
	v_pk_fma_f32 v[60:61], v[124:125], v[204:205], v[60:61]
	v_pk_fma_f32 v[62:63], v[126:127], v[206:207], v[62:63]
	v_pk_mul_f32 v[254:255], v[48:49], v[48:49]
	v_pk_fma_f32 v[254:255], v[50:51], v[50:51], v[254:255]
	v_pk_fma_f32 v[254:255], v[52:53], v[52:53], v[254:255]
	v_pk_fma_f32 v[254:255], v[54:55], v[54:55], v[254:255]
	v_pk_fma_f32 v[254:255], v[56:57], v[56:57], v[254:255]
	v_pk_fma_f32 v[254:255], v[58:59], v[58:59], v[254:255]
	v_pk_fma_f32 v[254:255], v[60:61], v[60:61], v[254:255]
	v_pk_fma_f32 v[254:255], v[62:63], v[62:63], v[254:255]
	v_add_f32_e32 v248, v248, v249
	v_add_f32_e32 v250, v250, v251
	v_add_f32_e32 v252, v252, v253
	v_add_f32_e32 v254, v254, v255
	v_mov_b32_e32 v249, v248
	v_mov_b32_e32 v251, v250
	v_mov_b32_e32 v253, v252
	v_mov_b32_e32 v255, v254
	v_permlane32_swap_b32_e32 v248, v249
	v_permlane32_swap_b32_e32 v250, v251
	v_permlane32_swap_b32_e32 v252, v253
	v_permlane32_swap_b32_e32 v254, v255
	v_add_f32_e32 v248, v248, v249
	v_add_f32_e32 v250, v250, v251
	v_add_f32_e32 v252, v252, v253
	v_add_f32_e32 v254, v254, v255
	v_mov_b32_e32 v249, v248
	v_mov_b32_e32 v251, v250
	v_mov_b32_e32 v253, v252
	v_mov_b32_e32 v255, v254
	v_permlane16_swap_b32_e32 v248, v249
	v_permlane16_swap_b32_e32 v250, v251
	v_permlane16_swap_b32_e32 v252, v253
	v_permlane16_swap_b32_e32 v254, v255
	v_add_f32_e32 v248, v248, v249
	v_add_f32_e32 v250, v250, v251
	v_add_f32_e32 v252, v252, v253
	v_add_f32_e32 v254, v254, v255
	v_add_f32_dpp v248, v248, v248 quad_perm:[1,0,3,2] row_mask:0xf bank_mask:0xf bound_ctrl:1
	v_add_f32_dpp v250, v250, v250 quad_perm:[1,0,3,2] row_mask:0xf bank_mask:0xf bound_ctrl:1
	v_add_f32_dpp v252, v252, v252 quad_perm:[1,0,3,2] row_mask:0xf bank_mask:0xf bound_ctrl:1
	v_add_f32_dpp v254, v254, v254 quad_perm:[1,0,3,2] row_mask:0xf bank_mask:0xf bound_ctrl:1
	v_add_f32_dpp v248, v248, v248 quad_perm:[2,3,0,1] row_mask:0xf bank_mask:0xf bound_ctrl:1
	v_add_f32_dpp v250, v250, v250 quad_perm:[2,3,0,1] row_mask:0xf bank_mask:0xf bound_ctrl:1
	v_add_f32_dpp v252, v252, v252 quad_perm:[2,3,0,1] row_mask:0xf bank_mask:0xf bound_ctrl:1
	v_add_f32_dpp v254, v254, v254 quad_perm:[2,3,0,1] row_mask:0xf bank_mask:0xf bound_ctrl:1
	v_add_f32_dpp v248, v248, v248 row_half_mirror row_mask:0xf bank_mask:0xf bound_ctrl:1
	v_add_f32_dpp v250, v250, v250 row_half_mirror row_mask:0xf bank_mask:0xf bound_ctrl:1
	v_add_f32_dpp v252, v252, v252 row_half_mirror row_mask:0xf bank_mask:0xf bound_ctrl:1
	v_add_f32_dpp v254, v254, v254 row_half_mirror row_mask:0xf bank_mask:0xf bound_ctrl:1
	v_add_f32_dpp v248, v248, v248 row_mirror row_mask:0xf bank_mask:0xf bound_ctrl:1
	v_add_f32_dpp v250, v250, v250 row_mirror row_mask:0xf bank_mask:0xf bound_ctrl:1
	v_add_f32_dpp v252, v252, v252 row_mirror row_mask:0xf bank_mask:0xf bound_ctrl:1
	v_add_f32_dpp v254, v254, v254 row_mirror row_mask:0xf bank_mask:0xf bound_ctrl:1
	v_fmamk_f32 v248, v248, 0x3a800000, v243
	v_fmamk_f32 v250, v250, 0x3a800000, v243
	v_fmamk_f32 v252, v252, 0x3a800000, v243
	v_fmamk_f32 v254, v254, 0x3a800000, v243
	v_rsq_f32_e32 v248, v248
	v_rsq_f32_e32 v250, v250
	v_rsq_f32_e32 v252, v252
	v_rsq_f32_e32 v254, v254
	s_nop 0
; __device__ __forceinline__ void peer_tile(const Args& A, LAS unsigned char* lds, int tile) {
;     ...
;             const float rstd = rsqrtf(wave_sum(ss) * (1.f / 1024.f) + 1e-6f);
; #pragma unroll
;             for (int j = 0; j < 4; ++j) { const f32x4 fg = *(const f32x4*)(A.final_g + 16 * lane + 4 * j); *(f32x4*)(orow + 4 * j) = xv[j] * rstd * fg; }
	v_pk_mul_f32 v[0:1], v[0:1], v[248:249] op_sel_hi:[1,0]
	v_pk_mul_f32 v[2:3], v[2:3], v[248:249] op_sel_hi:[1,0]
	v_pk_mul_f32 v[4:5], v[4:5], v[248:249] op_sel_hi:[1,0]
	v_pk_mul_f32 v[6:7], v[6:7], v[248:249] op_sel_hi:[1,0]
	v_pk_mul_f32 v[8:9], v[8:9], v[248:249] op_sel_hi:[1,0]
	v_pk_mul_f32 v[10:11], v[10:11], v[248:249] op_sel_hi:[1,0]
	v_pk_mul_f32 v[12:13], v[12:13], v[248:249] op_sel_hi:[1,0]
	v_pk_mul_f32 v[14:15], v[14:15], v[248:249] op_sel_hi:[1,0]
	v_pk_mul_f32 v[0:1], v[216:217], v[0:1]
	v_pk_mul_f32 v[2:3], v[218:219], v[2:3]
	v_pk_mul_f32 v[4:5], v[220:221], v[4:5]
	v_pk_mul_f32 v[6:7], v[222:223], v[6:7]
	v_pk_mul_f32 v[8:9], v[224:225], v[8:9]
	v_pk_mul_f32 v[10:11], v[226:227], v[10:11]
	v_pk_mul_f32 v[12:13], v[228:229], v[12:13]
	v_pk_mul_f32 v[14:15], v[230:231], v[14:15]
	global_store_dwordx4 v246, v[0:3], s[56:57]
	global_store_dwordx4 v246, v[4:7], s[56:57] offset:16
	global_store_dwordx4 v246, v[8:11], s[56:57] offset:32
	global_store_dwordx4 v246, v[12:15], s[56:57] offset:48
	v_pk_mul_f32 v[16:17], v[16:17], v[250:251] op_sel_hi:[1,0]
	v_pk_mul_f32 v[18:19], v[18:19], v[250:251] op_sel_hi:[1,0]
	v_pk_mul_f32 v[20:21], v[20:21], v[250:251] op_sel_hi:[1,0]
	v_pk_mul_f32 v[22:23], v[22:23], v[250:251] op_sel_hi:[1,0]
	v_pk_mul_f32 v[24:25], v[24:25], v[250:251] op_sel_hi:[1,0]
	v_pk_mul_f32 v[26:27], v[26:27], v[250:251] op_sel_hi:[1,0]
	v_pk_mul_f32 v[28:29], v[28:29], v[250:251] op_sel_hi:[1,0]
	v_pk_mul_f32 v[30:31], v[30:31], v[250:251] op_sel_hi:[1,0]
	v_pk_mul_f32 v[16:17], v[216:217], v[16:17]
	v_pk_mul_f32 v[18:19], v[218:219], v[18:19]
	v_pk_mul_f32 v[20:21], v[220:221], v[20:21]
	v_pk_mul_f32 v[22:23], v[222:223], v[22:23]
	v_pk_mul_f32 v[24:25], v[224:225], v[24:25]
	v_pk_mul_f32 v[26:27], v[226:227], v[26:27]
	v_pk_mul_f32 v[28:29], v[228:229], v[28:29]
	v_pk_mul_f32 v[30:31], v[230:231], v[30:31]
	global_store_dwordx4 v246, v[16:19], s[58:59]
	global_store_dwordx4 v246, v[20:23], s[58:59] offset:16
	global_store_dwordx4 v246, v[24:27], s[58:59] offset:32
	global_store_dwordx4 v246, v[28:31], s[58:59] offset:48
	v_pk_mul_f32 v[32:33], v[32:33], v[252:253] op_sel_hi:[1,0]
	v_pk_mul_f32 v[34:35], v[34:35], v[252:253] op_sel_hi:[1,0]
	v_pk_mul_f32 v[36:37], v[36:37], v[252:253] op_sel_hi:[1,0]
	v_pk_mul_f32 v[38:39], v[38:39], v[252:253] op_sel_hi:[1,0]
	v_pk_mul_f32 v[40:41], v[40:41], v[252:253] op_sel_hi:[1,0]
	v_pk_mul_f32 v[42:43], v[42:43], v[252:253] op_sel_hi:[1,0]
	v_pk_mul_f32 v[44:45], v[44:45], v[252:253] op_sel_hi:[1,0]
	v_pk_mul_f32 v[46:47], v[46:47], v[252:253] op_sel_hi:[1,0]
	v_pk_mul_f32 v[32:33], v[216:217], v[32:33]
	v_pk_mul_f32 v[34:35], v[218:219], v[34:35]
	v_pk_mul_f32 v[36:37], v[220:221], v[36:37]
	v_pk_mul_f32 v[38:39], v[222:223], v[38:39]
	v_pk_mul_f32 v[40:41], v[224:225], v[40:41]
	v_pk_mul_f32 v[42:43], v[226:227], v[42:43]
	v_pk_mul_f32 v[44:45], v[228:229], v[44:45]
	v_pk_mul_f32 v[46:47], v[230:231], v[46:47]
	global_store_dwordx4 v246, v[32:35], s[60:61]
	global_store_dwordx4 v246, v[36:39], s[60:61] offset:16
	global_store_dwordx4 v246, v[40:43], s[60:61] offset:32
	global_store_dwordx4 v246, v[44:47], s[60:61] offset:48
	v_pk_mul_f32 v[48:49], v[48:49], v[254:255] op_sel_hi:[1,0]
	v_pk_mul_f32 v[50:51], v[50:51], v[254:255] op_sel_hi:[1,0]
	v_pk_mul_f32 v[52:53], v[52:53], v[254:255] op_sel_hi:[1,0]
	v_pk_mul_f32 v[54:55], v[54:55], v[254:255] op_sel_hi:[1,0]
	v_pk_mul_f32 v[56:57], v[56:57], v[254:255] op_sel_hi:[1,0]
	v_pk_mul_f32 v[58:59], v[58:59], v[254:255] op_sel_hi:[1,0]
	v_pk_mul_f32 v[60:61], v[60:61], v[254:255] op_sel_hi:[1,0]
	v_pk_mul_f32 v[62:63], v[62:63], v[254:255] op_sel_hi:[1,0]
	v_pk_mul_f32 v[48:49], v[216:217], v[48:49]
	v_pk_mul_f32 v[50:51], v[218:219], v[50:51]
	v_pk_mul_f32 v[52:53], v[220:221], v[52:53]
	v_pk_mul_f32 v[54:55], v[222:223], v[54:55]
	v_pk_mul_f32 v[56:57], v[224:225], v[56:57]
	v_pk_mul_f32 v[58:59], v[226:227], v[58:59]
	v_pk_mul_f32 v[60:61], v[228:229], v[60:61]
	v_pk_mul_f32 v[62:63], v[230:231], v[62:63]
	global_store_dwordx4 v246, v[48:51], s[62:63]
	global_store_dwordx4 v246, v[52:55], s[62:63] offset:16
	global_store_dwordx4 v246, v[56:59], s[62:63] offset:32
	global_store_dwordx4 v246, v[60:63], s[62:63] offset:48
	s_nop 1
	v_mov_b32_e32 v113, 0
	v_mbcnt_lo_u32_b32 v215, -1, 0
	v_mbcnt_hi_u32_b32 v215, -1, v215
	v_and_b32_e32 v216, 64, v215
	v_add_u32_e32 v216, 64, v216
	v_xor_b32_e32 v217, 16, v215
	v_xor_b32_e32 v218, 32, v215
	s_branch .LBB0_698

